# peeled first K iteration (C=0, no accumulator zero-fill) + RG weight conversion loads issued together
# speedup vs baseline: 1.0325x; 1.0071x over previous
; __device__ __forceinline__ bf16_t f2bf(float f) { unsigned u = __float_as_uint(f); u += 0x7FFFu + ((u >> 16) & 1u); return (bf16_t)(u >> 16); }
;     ...
;     for (int t_ = first; t_ < ntile * ((REP & 1) + 1); t_ += gridDim.x) { const int t = t_ % ntile;
;         const int r0 = (t / nkt) * 64, k0 = (t % nkt) * 64;
;         __syncthreads();
; #pragma unroll
;         for (int i = 0; i < 8; ++i) { const int kk = i * 8 + w; tile[kk * 65 + lane] = src(k0 + kk, r0 + lane); }
;         __syncthreads();
; #pragma unroll
;         for (int i = 0; i < 8; ++i) { const int j = i * 8 + w; Bt[(size_t)(r0 + j) * ld + k0 + lane] = f2bf(tile[lane * 65 + j]); }
; __device__ void convert_phase(unsigned char* smem, const Params& p, int l) {
;     ...
;       conv_tiles(tile, wt + W_RG, 2048, 512, 131, [=](int k, int r) { const int dir = r >> 10, cp = r & 1023, ch = (cp >> 5) * 16 + (cp & 15), hb = ch >> 6, jj = ch & 63;
;           if ((k >> 6) != hb) return 0.0f; const float* src = ((cp >> 4) & 1) ? wx : wa; return src[(((size_t)dir * 8 + hb) * 64 + (k & 63)) * 64 + jj]; }); }
.LBB0_340:
	s_or_b64 exec, exec, s[8:9]
	s_waitcnt vmcnt(0)
	ds_write_b32 v25, v32
	ds_write_b32 v25, v33 offset:2080
	ds_write_b32 v25, v34 offset:4160
	ds_write_b32 v25, v35 offset:6240
	ds_write_b32 v25, v36 offset:8320
	ds_write_b32 v25, v37 offset:10400
	ds_write_b32 v25, v38 offset:12480
	ds_write_b32 v25, v39 offset:14560
	s_waitcnt lgkmcnt(0)
	s_barrier
	ds_read2_b32 v[20:21], v11 offset1:8
	s_ashr_i32 s1, s0, 31
	v_lshl_add_u64 v[26:27], s[0:1], 1, v[2:3]
	s_add_i32 s10, s10, s5
	s_cmpk_lt_i32 s10, 0x100
	s_waitcnt lgkmcnt(0)
	v_bfe_u32 v28, v20, 16, 1
	v_add3_u32 v20, v20, v28, s88
	v_add_u32_e32 v28, s11, v7
	v_ashrrev_i32_e32 v29, 31, v28
	v_lshlrev_b64 v[28:29], 10, v[28:29]
	v_lshl_add_u64 v[28:29], v[26:27], 0, v[28:29]
	global_store_short_d16_hi v[28:29], v20, off
	v_bfe_u32 v20, v21, 16, 1
	ds_read2_b32 v[28:29], v11 offset0:16 offset1:24
	v_add3_u32 v30, v21, v20, s88
	v_add_u32_e32 v20, s11, v13
	v_ashrrev_i32_e32 v21, 31, v20
	v_lshlrev_b64 v[20:21], 10, v[20:21]
	v_lshl_add_u64 v[20:21], v[26:27], 0, v[20:21]
	global_store_short_d16_hi v[20:21], v30, off
	s_waitcnt lgkmcnt(0)
	v_bfe_u32 v20, v28, 16, 1
	v_add3_u32 v28, v28, v20, s88
	v_add_u32_e32 v20, s11, v15
	v_ashrrev_i32_e32 v21, 31, v20
	v_lshlrev_b64 v[20:21], 10, v[20:21]
	v_lshl_add_u64 v[20:21], v[26:27], 0, v[20:21]
	global_store_short_d16_hi v[20:21], v28, off
	v_bfe_u32 v20, v29, 16, 1
	v_add3_u32 v30, v29, v20, s88
	ds_read2_b32 v[28:29], v11 offset0:32 offset1:40
	v_add_u32_e32 v20, s11, v17
	v_ashrrev_i32_e32 v21, 31, v20
	v_lshlrev_b64 v[20:21], 10, v[20:21]
	v_lshl_add_u64 v[20:21], v[26:27], 0, v[20:21]
	global_store_short_d16_hi v[20:21], v30, off
	s_waitcnt lgkmcnt(0)
	v_bfe_u32 v20, v28, 16, 1
	v_add3_u32 v28, v28, v20, s88
	v_add_u32_e32 v20, s11, v19
	v_ashrrev_i32_e32 v21, 31, v20
	v_lshlrev_b64 v[20:21], 10, v[20:21]
	v_lshl_add_u64 v[20:21], v[26:27], 0, v[20:21]
	global_store_short_d16_hi v[20:21], v28, off
	v_bfe_u32 v20, v29, 16, 1
	v_add3_u32 v30, v29, v20, s88
	ds_read2_b32 v[28:29], v11 offset0:48 offset1:56
	v_add_u32_e32 v20, s11, v22
	v_ashrrev_i32_e32 v21, 31, v20
	v_lshlrev_b64 v[20:21], 10, v[20:21]
	v_lshl_add_u64 v[20:21], v[26:27], 0, v[20:21]
	global_store_short_d16_hi v[20:21], v30, off
	s_waitcnt lgkmcnt(0)
	v_bfe_u32 v20, v28, 16, 1
	v_add3_u32 v28, v28, v20, s88
	v_add_u32_e32 v20, s11, v23
	v_ashrrev_i32_e32 v21, 31, v20
	v_lshlrev_b64 v[20:21], 10, v[20:21]
	v_lshl_add_u64 v[20:21], v[26:27], 0, v[20:21]
	global_store_short_d16_hi v[20:21], v28, off
	v_bfe_u32 v20, v29, 16, 1
	v_add3_u32 v28, v29, v20, s88
	v_add_u32_e32 v20, s11, v24
	v_ashrrev_i32_e32 v21, 31, v20
	v_lshlrev_b64 v[20:21], 10, v[20:21]
	v_lshl_add_u64 v[20:21], v[26:27], 0, v[20:21]
	global_store_short_d16_hi v[20:21], v28, off
	s_cbranch_scc0 .LBB0_357
.LBB0_341:
	s_ashr_i32 s0, s10, 31
	s_lshr_b32 s0, s0, 24
	s_add_i32 s0, s10, s0
	s_and_b32 s0, s0, 0xff00
	s_sub_i32 s0, s10, s0
	s_sext_i32_i16 s1, s0
	s_bfe_u32 s1, s1, 0x3001c
	s_add_i32 s1, s0, s1
	s_sext_i32_i16 s6, s1
	s_ashr_i32 s7, s6, 3
	s_and_b32 s1, s1, 0xfff8
	s_lshl_b32 s11, s7, 6
	s_sub_i32 s0, s0, s1
	s_sext_i32_i16 s0, s0
	v_or_b32_e32 v20, s11, v5
	s_lshl_b32 s0, s0, 6
	v_lshrrev_b32_e32 v20, 1, v20
	s_ashr_i32 s6, s6, 7
	s_bfe_u32 s1, s7, 0x30001
	v_and_or_b32 v20, v20, 48, v9
	s_ashr_i32 s7, s6, 31
	v_add_u32_e32 v26, s0, v7
	s_lshl_b64 s[6:7], s[6:7], 9
	s_lshl_b32 s8, s1, 6
	v_lshlrev_b32_e32 v184, 2, v20
	v_ashrrev_i32_e32 v26, 6, v26
	s_or_b32 s6, s6, s8
	v_lshl_add_u64 v[20:21], v[0:1], 0, v[184:185]
	v_cmp_eq_u32_e32 vcc, s1, v26
	v_mov_b32_e32 v32, 0
	v_mov_b32_e32 v33, 0
	v_mov_b32_e32 v34, 0
	v_mov_b32_e32 v35, 0
	v_mov_b32_e32 v36, 0
	v_mov_b32_e32 v37, 0
	v_mov_b32_e32 v38, 0
	v_mov_b32_e32 v39, 0
	s_barrier
	s_and_saveexec_b64 s[8:9], vcc
	s_cbranch_execz .LBB0_343
	v_mov_b32_e32 v29, s7
	v_or_b32_e32 v28, s6, v4
	v_lshlrev_b64 v[28:29], 8, v[28:29]
	v_lshl_add_u64 v[28:29], v[20:21], 0, v[28:29]
	global_load_dword v32, v[28:29], off
.LBB0_343:
	s_or_b64 exec, exec, s[8:9]
	v_add_u32_e32 v27, s0, v13
	v_ashrrev_i32_e32 v27, 6, v27
	v_cmp_eq_u32_e32 vcc, s1, v27
	s_and_saveexec_b64 s[8:9], vcc
	s_cbranch_execz .LBB0_345
	v_mov_b32_e32 v27, s7
	v_or_b32_e32 v26, s6, v6
	v_lshlrev_b64 v[26:27], 8, v[26:27]
	v_lshl_add_u64 v[26:27], v[20:21], 0, v[26:27]
	global_load_dword v33, v[26:27], off
.LBB0_345:
	s_or_b64 exec, exec, s[8:9]
	v_add_u32_e32 v26, s0, v15
	v_ashrrev_i32_e32 v26, 6, v26
	v_cmp_eq_u32_e32 vcc, s1, v26
	v_mov_b32_e32 v26, 0
	v_mov_b32_e32 v27, 0
	s_and_saveexec_b64 s[8:9], vcc
	s_cbranch_execz .LBB0_347
	v_mov_b32_e32 v29, s7
	v_or_b32_e32 v28, s6, v8
	v_lshlrev_b64 v[28:29], 8, v[28:29]
	v_lshl_add_u64 v[28:29], v[20:21], 0, v[28:29]
	global_load_dword v34, v[28:29], off
.LBB0_347:
	s_or_b64 exec, exec, s[8:9]
	v_add_u32_e32 v27, s0, v17
	v_ashrrev_i32_e32 v27, 6, v27
	v_cmp_eq_u32_e32 vcc, s1, v27
	s_and_saveexec_b64 s[8:9], vcc
	s_cbranch_execz .LBB0_349
	v_mov_b32_e32 v27, s7
	v_or_b32_e32 v26, s6, v10
	v_lshlrev_b64 v[26:27], 8, v[26:27]
	v_lshl_add_u64 v[26:27], v[20:21], 0, v[26:27]
	global_load_dword v35, v[26:27], off
.LBB0_349:
	s_or_b64 exec, exec, s[8:9]
	v_add_u32_e32 v26, s0, v19
	v_ashrrev_i32_e32 v26, 6, v26
	v_cmp_eq_u32_e32 vcc, s1, v26
	v_mov_b32_e32 v26, 0
	v_mov_b32_e32 v27, 0
	s_and_saveexec_b64 s[8:9], vcc
	s_cbranch_execz .LBB0_351
	v_mov_b32_e32 v29, s7
	v_or_b32_e32 v28, s6, v12
	v_lshlrev_b64 v[28:29], 8, v[28:29]
	v_lshl_add_u64 v[28:29], v[20:21], 0, v[28:29]
	global_load_dword v36, v[28:29], off
.LBB0_351:
	s_or_b64 exec, exec, s[8:9]
	v_add_u32_e32 v27, s0, v22
	v_ashrrev_i32_e32 v27, 6, v27
	v_cmp_eq_u32_e32 vcc, s1, v27
	s_and_saveexec_b64 s[8:9], vcc
	s_cbranch_execz .LBB0_353
	v_mov_b32_e32 v27, s7
	v_or_b32_e32 v26, s6, v14
	v_lshlrev_b64 v[26:27], 8, v[26:27]
	v_lshl_add_u64 v[26:27], v[20:21], 0, v[26:27]
	global_load_dword v37, v[26:27], off
.LBB0_353:
	s_or_b64 exec, exec, s[8:9]
	v_add_u32_e32 v26, s0, v23
	v_ashrrev_i32_e32 v26, 6, v26
	v_cmp_eq_u32_e32 vcc, s1, v26
	v_mov_b32_e32 v26, 0
	v_mov_b32_e32 v27, 0
	s_and_saveexec_b64 s[8:9], vcc
	s_cbranch_execz .LBB0_355
	v_mov_b32_e32 v29, s7
	v_or_b32_e32 v28, s6, v16
	v_lshlrev_b64 v[28:29], 8, v[28:29]
	v_lshl_add_u64 v[28:29], v[20:21], 0, v[28:29]
	global_load_dword v38, v[28:29], off
.LBB0_355:
	s_or_b64 exec, exec, s[8:9]
	v_add_u32_e32 v27, s0, v24
	v_ashrrev_i32_e32 v27, 6, v27
	v_cmp_eq_u32_e32 vcc, s1, v27
	s_and_saveexec_b64 s[8:9], vcc
	s_cbranch_execz .LBB0_340
	v_mov_b32_e32 v27, s7
	v_or_b32_e32 v26, s6, v18
	v_lshlrev_b64 v[26:27], 8, v[26:27]
	v_lshl_add_u64 v[20:21], v[20:21], 0, v[26:27]
	global_load_dword v39, v[20:21], off
	s_branch .LBB0_340

; #define PG8_STAGE(bufoff, gbase, voff) do { _Pragma("unroll") for (int _i = 0; _i < 2; ++_i) \
;         __builtin_amdgcn_global_load_lds((const unsigned*)((const char*)(gbase) + (voff)[_i]), (LAS unsigned*)(lds + (bufoff) + ldsw + _i * 8192), 16, 0, 0); } while (0)
; #define PG8_LDA(dst, b, h) do { _Pragma("unroll") for (int m = 0; m < 4; ++m) _Pragma("unroll") for (int k = 0; k < 2; ++k) dst[m][k] = *(const LAS bf16x8*)(lds + PG8_SA(b, h) + aoff + m * 2048 + k * 1024); } while (0)
; #define PG8_LDB(dst, b, h) do { _Pragma("unroll") for (int n = 0; n < 2; ++n) _Pragma("unroll") for (int k = 0; k < 2; ++k) dst[n][k] = *(const LAS bf16x8*)(lds + PG8_SB(b, h) + boff + n * 2048 + k * 1024); } while (0)
; #define PG8_MMA(ai, bj, At, Bt) do { __builtin_amdgcn_s_setprio(1); _Pragma("unroll") for (int m = 0; m < 4; ++m) _Pragma("unroll") for (int n = 0; n < 2; ++n) _Pragma("unroll") for (int k = 0; k < 2; ++k) \
;         acc[ai][bj][m][n] = __builtin_amdgcn_mfma_f32_16x16x32_bf16(Bt[n][k], At[m][k], acc[ai][bj][m][n], 0, 0, 0); __builtin_amdgcn_s_setprio(0); } while (0)
; #define PG8_WAIT_V(n) asm volatile("s_waitcnt vmcnt(" #n ")" ::: "memory")
; #define PG8_WAIT_L(n) asm volatile("s_waitcnt lgkmcnt(" #n ")" ::: "memory")
; template <class Epi>
; __device__ __forceinline__ void gemm_phase(LAS unsigned char* lds, const Gemm g, const StaticOrder& S, const Epi& E, const bool perm) {
;     ...
;             PG8_LDB(B0, 0, 0); PG8_SCHED; PG8_LDA(At, 0, 0); PG8_STAGE(PG8_SA(1, 1), a1 + hstep, voffA);
;             PG8_WAIT_L(8); PG8_BAR; PG8_WAIT_L(0); PG8_MMA(0, 0, At, B0); PG8_BAR; PG8_SCHED;
;             PG8_LDB(B1, 0, 1); PG8_STAGE(PG8_SB(0, 0), b2, voffB);
;             PG8_BAR; PG8_WAIT_L(0); PG8_MMA(0, 1, At, B1); PG8_BAR;
;             PG8_LDA(At, 0, 1); PG8_STAGE(PG8_SA(0, 0), a2, voffA);
;             PG8_BAR; PG8_WAIT_L(0); PG8_MMA(1, 0, At, B0); PG8_BAR; PG8_SCHED;
;             PG8_STAGE(PG8_SB(0, 1), b2 + hstep, voffB);
;             PG8_WAIT_V(6); PG8_BAR; PG8_MMA(1, 1, At, B1); PG8_BAR;
;     ...
; #pragma unroll
;         for (int a = 0; a < 2; ++a)
; #pragma unroll
;             for (int b = 0; b < 2; ++b)
; #pragma unroll
;                 for (int m = 0; m < 4; ++m)
; #pragma unroll
;                     for (int n = 0; n < 2; ++n) acc[a][b][m][n] = (f32x4){0.f, 0.f, 0.f, 0.f};
;         cur = nxt; cA = nA; cB = nB; ++ui;
.LBB0_461:
	s_lshl_b32 s51, s70, 8
	s_add_u32 s6, s6, 0x80
	s_addc_u32 s7, s7, 0
	s_add_u32 s55, s22, 0x100
	v_lshl_add_u32 v218, s46, 8, v244
	v_or_b32_e32 v220, s51, v246
	s_addc_u32 s78, s23, 0
	s_mov_b32 s79, 0
	s_mov_b32 s60, 0
	s_branch .LBB0_463
.Lk_first:
	s_add_i32 s61, s60, 2
	s_add_u32 s22, s6, 0x80
	s_addc_u32 s23, s7, 0
	s_add_i32 s40, 0, 0x10000
	v_add_u32_e32 v140, s40, v245
	s_waitcnt lgkmcnt(0)
	ds_read_b128 v[128:131], v140
	ds_read_b128 v[132:135], v140 offset:1024
	ds_read_b128 v[136:139], v140 offset:2048
	ds_read_b128 v[140:143], v140 offset:3072
	s_cmp_eq_u32 s27, s60
	s_cselect_b32 s23, s1, s23
	s_cselect_b32 s22, s0, s22
	s_cselect_b32 s47, s13, s78
	s_cselect_b32 s46, s12, s55
	v_lshl_add_u64 v[176:177], s[6:7], 0, v[214:215]
	s_add_i32 m0, s36, 0xc000
	ds_read_b128 v[144:147], v248
	ds_read_b128 v[148:151], v248 offset:1024
	ds_read_b128 v[152:155], v248 offset:2048
	ds_read_b128 v[156:159], v248 offset:3072
	ds_read_b128 v[160:163], v248 offset:4096
	ds_read_b128 v[164:167], v248 offset:5120
	ds_read_b128 v[168:171], v248 offset:6144
	ds_read_b128 v[172:175], v248 offset:7168
	global_load_lds_dwordx4 v[176:177], off
	v_lshl_add_u64 v[176:177], s[6:7], 0, v[216:217]
	s_add_i32 m0, s36, 0xe000
	s_nop 0
	global_load_lds_dwordx4 v[176:177], off
	s_add_i32 s60, 0, 0x14000
	s_add_i32 s40, s40, s31
	v_add_u32_e32 v184, s60, v245
	ds_read_b128 v[176:179], v184
	ds_read_b128 v[180:183], v184 offset:1024
	ds_read_b128 v[222:225], v184 offset:2048
	ds_read_b128 v[226:229], v184 offset:3072
	s_waitcnt vmcnt(8)
	s_waitcnt lgkmcnt(0)
	s_barrier
	s_setprio 1
	v_mfma_f32_16x16x32_bf16 v[124:127], v[128:131], v[144:147], 0
	v_mfma_f32_16x16x32_bf16 v[120:123], v[136:139], v[144:147], 0
	v_mfma_f32_16x16x32_bf16 v[108:111], v[128:131], v[152:155], 0
	v_mfma_f32_16x16x32_bf16 v[104:107], v[136:139], v[152:155], 0
	v_mfma_f32_16x16x32_bf16 v[92:95], v[128:131], v[160:163], 0
	v_mfma_f32_16x16x32_bf16 v[88:91], v[136:139], v[160:163], 0
	v_mfma_f32_16x16x32_bf16 v[76:79], v[128:131], v[168:171], 0
	v_mfma_f32_16x16x32_bf16 v[72:75], v[136:139], v[168:171], 0
	v_mfma_f32_16x16x32_bf16 v[124:127], v[132:135], v[148:151], v[124:127]
	v_mfma_f32_16x16x32_bf16 v[120:123], v[140:143], v[148:151], v[120:123]
	v_mfma_f32_16x16x32_bf16 v[108:111], v[132:135], v[156:159], v[108:111]
	v_mfma_f32_16x16x32_bf16 v[104:107], v[140:143], v[156:159], v[104:107]
	v_mfma_f32_16x16x32_bf16 v[92:95], v[132:135], v[164:167], v[92:95]
	v_mfma_f32_16x16x32_bf16 v[88:91], v[140:143], v[164:167], v[88:91]
	v_mfma_f32_16x16x32_bf16 v[76:79], v[132:135], v[172:175], v[76:79]
	v_mfma_f32_16x16x32_bf16 v[72:75], v[140:143], v[172:175], v[72:75]
	v_mfma_f32_16x16x32_bf16 v[116:119], v[176:179], v[144:147], 0
	v_mfma_f32_16x16x32_bf16 v[112:115], v[222:225], v[144:147], 0
	v_mfma_f32_16x16x32_bf16 v[100:103], v[176:179], v[152:155], 0
	v_mfma_f32_16x16x32_bf16 v[96:99], v[222:225], v[152:155], 0
	v_mfma_f32_16x16x32_bf16 v[84:87], v[176:179], v[160:163], 0
	v_mfma_f32_16x16x32_bf16 v[80:83], v[222:225], v[160:163], 0
	v_mfma_f32_16x16x32_bf16 v[68:71], v[176:179], v[168:171], 0
	v_mfma_f32_16x16x32_bf16 v[64:67], v[222:225], v[168:171], 0
	v_mfma_f32_16x16x32_bf16 v[116:119], v[180:183], v[148:151], v[116:119]
	v_mfma_f32_16x16x32_bf16 v[112:115], v[226:229], v[148:151], v[112:115]
	v_mfma_f32_16x16x32_bf16 v[100:103], v[180:183], v[156:159], v[100:103]
	v_mfma_f32_16x16x32_bf16 v[96:99], v[226:229], v[156:159], v[96:99]
	v_mfma_f32_16x16x32_bf16 v[84:87], v[180:183], v[164:167], v[84:87]
	v_mfma_f32_16x16x32_bf16 v[80:83], v[226:229], v[164:167], v[80:83]
	v_mfma_f32_16x16x32_bf16 v[68:71], v[180:183], v[172:175], v[68:71]
	v_mfma_f32_16x16x32_bf16 v[64:67], v[226:229], v[172:175], v[64:67]
	s_setprio 0
	s_barrier
	ds_read_b128 v[144:147], v248 offset:16384
	ds_read_b128 v[148:151], v248 offset:17408
	ds_read_b128 v[152:155], v248 offset:18432
	ds_read_b128 v[156:159], v248 offset:19456
	ds_read_b128 v[160:163], v248 offset:20480
	ds_read_b128 v[164:167], v248 offset:21504
	ds_read_b128 v[168:171], v248 offset:22528
	ds_read_b128 v[172:175], v248 offset:23552
	v_lshl_add_u64 v[230:231], s[46:47], 0, v[212:213]
	s_mov_b32 m0, s40
	s_nop 0
	global_load_lds_dwordx4 v[230:231], off
	v_lshl_add_u64 v[232:233], s[46:47], 0, v[208:209]
	s_add_i32 m0, s40, 0x2000
	s_nop 0
	global_load_lds_dwordx4 v[232:233], off
	v_lshl_add_u64 v[250:251], s[22:23], 0, v[210:211]
	s_mov_b32 m0, s36
	s_nop 0
	global_load_lds_dwordx4 v[250:251], off
	v_lshl_add_u64 v[252:253], s[22:23], 0, v[206:207]
	s_mov_b32 m0, s37
	s_nop 0
	global_load_lds_dwordx4 v[252:253], off
	s_add_u32 s40, s46, s80
	s_addc_u32 s41, s47, s81
	s_add_i32 s46, s60, s31
	v_lshl_add_u64 v[238:239], s[40:41], 0, v[212:213]
	s_mov_b32 m0, s46
	v_lshl_add_u64 v[240:241], s[40:41], 0, v[208:209]
	global_load_lds_dwordx4 v[238:239], off
	s_add_i32 m0, s46, 0x2000
	s_nop 0
	global_load_lds_dwordx4 v[240:241], off
	s_waitcnt vmcnt(8)
	s_waitcnt lgkmcnt(0)
	s_barrier
; #define PG8_STAGE(bufoff, gbase, voff) do { _Pragma("unroll") for (int _i = 0; _i < 2; ++_i) \
;         __builtin_amdgcn_global_load_lds((const unsigned*)((const char*)(gbase) + (voff)[_i]), (LAS unsigned*)(lds + (bufoff) + ldsw + _i * 8192), 16, 0, 0); } while (0)
; #define PG8_LDA(dst, b, h) do { _Pragma("unroll") for (int m = 0; m < 4; ++m) _Pragma("unroll") for (int k = 0; k < 2; ++k) dst[m][k] = *(const LAS bf16x8*)(lds + PG8_SA(b, h) + aoff + m * 2048 + k * 1024); } while (0)
; #define PG8_LDB(dst, b, h) do { _Pragma("unroll") for (int n = 0; n < 2; ++n) _Pragma("unroll") for (int k = 0; k < 2; ++k) dst[n][k] = *(const LAS bf16x8*)(lds + PG8_SB(b, h) + boff + n * 2048 + k * 1024); } while (0)
; #define PG8_MMA(ai, bj, At, Bt) do { __builtin_amdgcn_s_setprio(1); _Pragma("unroll") for (int m = 0; m < 4; ++m) _Pragma("unroll") for (int n = 0; n < 2; ++n) _Pragma("unroll") for (int k = 0; k < 2; ++k) \
;         acc[ai][bj][m][n] = __builtin_amdgcn_mfma_f32_16x16x32_bf16(Bt[n][k], At[m][k], acc[ai][bj][m][n], 0, 0, 0); __builtin_amdgcn_s_setprio(0); } while (0)
; #define PG8_WAIT_V(n) asm volatile("s_waitcnt vmcnt(" #n ")" ::: "memory")
; #define PG8_WAIT_L(n) asm volatile("s_waitcnt lgkmcnt(" #n ")" ::: "memory")
; #define PG8_BAR __builtin_amdgcn_s_barrier()
; #define PG8_SCHED __builtin_amdgcn_sched_barrier(0)
; template <class Epi>
; __device__ __forceinline__ void gemm_phase(LAS unsigned char* lds, const Gemm g, const StaticOrder& S, const Epi& E, const bool perm) {
;     ...
;             PG8_BAR; PG8_WAIT_L(0); PG8_MMA(1, 0, At, B0); PG8_BAR; PG8_SCHED;
;             PG8_STAGE(PG8_SB(0, 1), b2 + hstep, voffB);
;             PG8_WAIT_V(6); PG8_BAR; PG8_MMA(1, 1, At, B1); PG8_BAR;
;             PG8_LDB(B0, 1, 0); PG8_SCHED; PG8_LDA(At, 1, 0); PG8_STAGE(PG8_SA(0, 1), a2 + hstep, voffA);
;             PG8_WAIT_L(8); PG8_BAR; PG8_WAIT_L(0); PG8_MMA(0, 0, At, B0); PG8_BAR; PG8_SCHED;
;             PG8_LDB(B1, 1, 1); PG8_STAGE(PG8_SB(1, 0), b3, voffB);
;             PG8_BAR; PG8_WAIT_L(0); PG8_MMA(0, 1, At, B1); PG8_BAR;
;             PG8_LDA(At, 1, 1); PG8_STAGE(PG8_SA(1, 0), a3, voffA);
;             PG8_BAR; PG8_WAIT_L(0); PG8_MMA(1, 0, At, B0); PG8_BAR; PG8_SCHED;
	s_setprio 1
	v_mfma_f32_16x16x32_bf16 v[60:63], v[128:131], v[144:147], 0
	v_mfma_f32_16x16x32_bf16 v[56:59], v[136:139], v[144:147], 0
	v_mfma_f32_16x16x32_bf16 v[44:47], v[128:131], v[152:155], 0
	v_mfma_f32_16x16x32_bf16 v[40:43], v[136:139], v[152:155], 0
	v_mfma_f32_16x16x32_bf16 v[28:31], v[128:131], v[160:163], 0
	v_mfma_f32_16x16x32_bf16 v[24:27], v[136:139], v[160:163], 0
	v_mfma_f32_16x16x32_bf16 v[12:15], v[128:131], v[168:171], 0
	v_mfma_f32_16x16x32_bf16 v[8:11], v[136:139], v[168:171], 0
	v_mfma_f32_16x16x32_bf16 v[60:63], v[132:135], v[148:151], v[60:63]
	v_mfma_f32_16x16x32_bf16 v[56:59], v[140:143], v[148:151], v[56:59]
	v_mfma_f32_16x16x32_bf16 v[44:47], v[132:135], v[156:159], v[44:47]
	v_mfma_f32_16x16x32_bf16 v[40:43], v[140:143], v[156:159], v[40:43]
	v_mfma_f32_16x16x32_bf16 v[28:31], v[132:135], v[164:167], v[28:31]
	v_mfma_f32_16x16x32_bf16 v[24:27], v[140:143], v[164:167], v[24:27]
	v_mfma_f32_16x16x32_bf16 v[12:15], v[132:135], v[172:175], v[12:15]
	v_mfma_f32_16x16x32_bf16 v[8:11], v[140:143], v[172:175], v[8:11]
	v_mfma_f32_16x16x32_bf16 v[52:55], v[176:179], v[144:147], 0
	v_mfma_f32_16x16x32_bf16 v[48:51], v[222:225], v[144:147], 0
	v_mfma_f32_16x16x32_bf16 v[36:39], v[176:179], v[152:155], 0
	v_mfma_f32_16x16x32_bf16 v[32:35], v[222:225], v[152:155], 0
	v_mfma_f32_16x16x32_bf16 v[20:23], v[176:179], v[160:163], 0
	v_mfma_f32_16x16x32_bf16 v[16:19], v[222:225], v[160:163], 0
	v_mfma_f32_16x16x32_bf16 v[4:7], v[176:179], v[168:171], 0
	v_mfma_f32_16x16x32_bf16 v[0:3], v[222:225], v[168:171], 0
	v_mfma_f32_16x16x32_bf16 v[52:55], v[180:183], v[148:151], v[52:55]
	v_mfma_f32_16x16x32_bf16 v[48:51], v[226:229], v[148:151], v[48:51]
	v_mfma_f32_16x16x32_bf16 v[36:39], v[180:183], v[156:159], v[36:39]
	v_mfma_f32_16x16x32_bf16 v[32:35], v[226:229], v[156:159], v[32:35]
	v_mfma_f32_16x16x32_bf16 v[20:23], v[180:183], v[164:167], v[20:23]
	v_mfma_f32_16x16x32_bf16 v[16:19], v[226:229], v[164:167], v[16:19]
	v_mfma_f32_16x16x32_bf16 v[4:7], v[180:183], v[172:175], v[4:7]
	v_mfma_f32_16x16x32_bf16 v[0:3], v[226:229], v[172:175], v[0:3]
	s_setprio 0
	s_add_i32 s40, 0, 0x18000
	v_add_u32_e32 v140, s40, v245
	s_barrier
	ds_read_b128 v[128:131], v140
	ds_read_b128 v[132:135], v140 offset:1024
	ds_read_b128 v[136:139], v140 offset:2048
	ds_read_b128 v[140:143], v140 offset:3072
	s_add_u32 s22, s22, s80
	s_addc_u32 s23, s23, s81
	s_mov_b32 m0, s34
	v_lshl_add_u64 v[176:177], s[22:23], 0, v[210:211]
	ds_read_b128 v[144:147], v248 offset:32768
	ds_read_b128 v[148:151], v248 offset:33792
	ds_read_b128 v[152:155], v248 offset:34816
	ds_read_b128 v[156:159], v248 offset:35840
	ds_read_b128 v[160:163], v248 offset:36864
	ds_read_b128 v[164:167], v248 offset:37888
	ds_read_b128 v[168:171], v248 offset:38912
	ds_read_b128 v[172:175], v248 offset:39936
	global_load_lds_dwordx4 v[176:177], off
	v_lshl_add_u64 v[176:177], s[22:23], 0, v[206:207]
	s_mov_b32 m0, s35
	s_nop 0
	global_load_lds_dwordx4 v[176:177], off
	s_add_i32 s22, 0, 0x1c000
	s_add_i32 s23, s40, s31
	v_add_u32_e32 v184, s22, v245
	ds_read_b128 v[176:179], v184
	ds_read_b128 v[180:183], v184 offset:1024
	ds_read_b128 v[222:225], v184 offset:2048
	ds_read_b128 v[226:229], v184 offset:3072
	s_waitcnt vmcnt(8)
	s_waitcnt lgkmcnt(0)
	s_barrier
	s_setprio 1
	v_mfma_f32_16x16x32_bf16 v[124:127], v[128:131], v[144:147], v[124:127]
	v_mfma_f32_16x16x32_bf16 v[120:123], v[136:139], v[144:147], v[120:123]
	v_mfma_f32_16x16x32_bf16 v[108:111], v[128:131], v[152:155], v[108:111]
	v_mfma_f32_16x16x32_bf16 v[104:107], v[136:139], v[152:155], v[104:107]
	v_mfma_f32_16x16x32_bf16 v[92:95], v[128:131], v[160:163], v[92:95]
	v_mfma_f32_16x16x32_bf16 v[88:91], v[136:139], v[160:163], v[88:91]
	v_mfma_f32_16x16x32_bf16 v[76:79], v[128:131], v[168:171], v[76:79]
	v_mfma_f32_16x16x32_bf16 v[72:75], v[136:139], v[168:171], v[72:75]
	v_mfma_f32_16x16x32_bf16 v[124:127], v[132:135], v[148:151], v[124:127]
	v_mfma_f32_16x16x32_bf16 v[120:123], v[140:143], v[148:151], v[120:123]
	v_mfma_f32_16x16x32_bf16 v[108:111], v[132:135], v[156:159], v[108:111]
	v_mfma_f32_16x16x32_bf16 v[104:107], v[140:143], v[156:159], v[104:107]
	v_mfma_f32_16x16x32_bf16 v[92:95], v[132:135], v[164:167], v[92:95]
	v_mfma_f32_16x16x32_bf16 v[88:91], v[140:143], v[164:167], v[88:91]
	v_mfma_f32_16x16x32_bf16 v[76:79], v[132:135], v[172:175], v[76:79]
	v_mfma_f32_16x16x32_bf16 v[72:75], v[140:143], v[172:175], v[72:75]
	v_mfma_f32_16x16x32_bf16 v[116:119], v[176:179], v[144:147], v[116:119]
	v_mfma_f32_16x16x32_bf16 v[112:115], v[222:225], v[144:147], v[112:115]
	v_mfma_f32_16x16x32_bf16 v[100:103], v[176:179], v[152:155], v[100:103]
	v_mfma_f32_16x16x32_bf16 v[96:99], v[222:225], v[152:155], v[96:99]
	v_mfma_f32_16x16x32_bf16 v[84:87], v[176:179], v[160:163], v[84:87]
	v_mfma_f32_16x16x32_bf16 v[80:83], v[222:225], v[160:163], v[80:83]
	v_mfma_f32_16x16x32_bf16 v[68:71], v[176:179], v[168:171], v[68:71]
	v_mfma_f32_16x16x32_bf16 v[64:67], v[222:225], v[168:171], v[64:67]
	v_mfma_f32_16x16x32_bf16 v[116:119], v[180:183], v[148:151], v[116:119]
	v_mfma_f32_16x16x32_bf16 v[112:115], v[226:229], v[148:151], v[112:115]
	v_mfma_f32_16x16x32_bf16 v[100:103], v[180:183], v[156:159], v[100:103]
	v_mfma_f32_16x16x32_bf16 v[96:99], v[226:229], v[156:159], v[96:99]
	v_mfma_f32_16x16x32_bf16 v[84:87], v[180:183], v[164:167], v[84:87]
	v_mfma_f32_16x16x32_bf16 v[80:83], v[226:229], v[164:167], v[80:83]
	v_mfma_f32_16x16x32_bf16 v[68:71], v[180:183], v[172:175], v[68:71]
	v_mfma_f32_16x16x32_bf16 v[64:67], v[226:229], v[172:175], v[64:67]
	s_setprio 0
	s_barrier
; #define PG8_STAGE(bufoff, gbase, voff) do { _Pragma("unroll") for (int _i = 0; _i < 2; ++_i) \
;         __builtin_amdgcn_global_load_lds((const unsigned*)((const char*)(gbase) + (voff)[_i]), (LAS unsigned*)(lds + (bufoff) + ldsw + _i * 8192), 16, 0, 0); } while (0)
; #define PG8_LDA(dst, b, h) do { _Pragma("unroll") for (int m = 0; m < 4; ++m) _Pragma("unroll") for (int k = 0; k < 2; ++k) dst[m][k] = *(const LAS bf16x8*)(lds + PG8_SA(b, h) + aoff + m * 2048 + k * 1024); } while (0)
; #define PG8_MMA(ai, bj, At, Bt) do { __builtin_amdgcn_s_setprio(1); _Pragma("unroll") for (int m = 0; m < 4; ++m) _Pragma("unroll") for (int n = 0; n < 2; ++n) _Pragma("unroll") for (int k = 0; k < 2; ++k) \
;         acc[ai][bj][m][n] = __builtin_amdgcn_mfma_f32_16x16x32_bf16(Bt[n][k], At[m][k], acc[ai][bj][m][n], 0, 0, 0); __builtin_amdgcn_s_setprio(0); } while (0)
; #define PG8_WAIT_V(n) asm volatile("s_waitcnt vmcnt(" #n ")" ::: "memory")
; #define PG8_WAIT_L(n) asm volatile("s_waitcnt lgkmcnt(" #n ")" ::: "memory")
; #define PG8_BAR __builtin_amdgcn_s_barrier()
; #define PG8_SCHED __builtin_amdgcn_sched_barrier(0)
; template <class Epi>
; __device__ __forceinline__ void gemm_phase(LAS unsigned char* lds, const Gemm g, const StaticOrder& S, const Epi& E, const bool perm) {
;     ...
;             PG8_LDA(At, 1, 1); PG8_STAGE(PG8_SA(1, 0), a3, voffA);
;             PG8_BAR; PG8_WAIT_L(0); PG8_MMA(1, 0, At, B0); PG8_BAR; PG8_SCHED;
;             PG8_STAGE(PG8_SB(1, 1), b3 + hstep, voffB);
;             PG8_WAIT_V(6); PG8_BAR; PG8_MMA(1, 1, At, B1); PG8_BAR;
;         }
	ds_read_b128 v[144:147], v248 offset:49152
	ds_read_b128 v[148:151], v248 offset:50176
	ds_read_b128 v[152:155], v248 offset:51200
	ds_read_b128 v[156:159], v248 offset:52224
	ds_read_b128 v[160:163], v248 offset:53248
	ds_read_b128 v[164:167], v248 offset:54272
	ds_read_b128 v[168:171], v248 offset:55296
	ds_read_b128 v[172:175], v248 offset:56320
	v_lshl_add_u64 v[230:231], v[230:231], 0, s[74:75]
	s_mov_b32 m0, s23
	s_nop 0
	global_load_lds_dwordx4 v[230:231], off
	v_lshl_add_u64 v[230:231], v[232:233], 0, s[74:75]
	s_add_i32 m0, s23, 0x2000
	s_nop 0
	global_load_lds_dwordx4 v[230:231], off
	v_lshl_add_u64 v[230:231], v[250:251], 0, s[74:75]
	s_mov_b32 m0, s14
	s_nop 0
	global_load_lds_dwordx4 v[230:231], off
	v_lshl_add_u64 v[230:231], v[252:253], 0, s[74:75]
	s_mov_b32 m0, s15
	s_nop 0
	global_load_lds_dwordx4 v[230:231], off
	s_add_i32 s22, s22, s31
	v_lshl_add_u64 v[230:231], v[238:239], 0, s[74:75]
	s_mov_b32 m0, s22
	s_nop 0
	global_load_lds_dwordx4 v[230:231], off
	v_lshl_add_u64 v[230:231], v[240:241], 0, s[74:75]
	s_add_i32 m0, s22, 0x2000
	s_nop 0
	global_load_lds_dwordx4 v[230:231], off
	s_waitcnt vmcnt(8)
	s_waitcnt lgkmcnt(0)
	s_barrier
	s_setprio 1
	v_mfma_f32_16x16x32_bf16 v[60:63], v[128:131], v[144:147], v[60:63]
	v_mfma_f32_16x16x32_bf16 v[56:59], v[136:139], v[144:147], v[56:59]
	v_mfma_f32_16x16x32_bf16 v[44:47], v[128:131], v[152:155], v[44:47]
	v_mfma_f32_16x16x32_bf16 v[40:43], v[136:139], v[152:155], v[40:43]
	v_mfma_f32_16x16x32_bf16 v[28:31], v[128:131], v[160:163], v[28:31]
	v_mfma_f32_16x16x32_bf16 v[24:27], v[136:139], v[160:163], v[24:27]
	v_mfma_f32_16x16x32_bf16 v[12:15], v[128:131], v[168:171], v[12:15]
	v_mfma_f32_16x16x32_bf16 v[8:11], v[136:139], v[168:171], v[8:11]
	v_mfma_f32_16x16x32_bf16 v[60:63], v[132:135], v[148:151], v[60:63]
	v_mfma_f32_16x16x32_bf16 v[56:59], v[140:143], v[148:151], v[56:59]
	v_mfma_f32_16x16x32_bf16 v[44:47], v[132:135], v[156:159], v[44:47]
	v_mfma_f32_16x16x32_bf16 v[40:43], v[140:143], v[156:159], v[40:43]
	v_mfma_f32_16x16x32_bf16 v[28:31], v[132:135], v[164:167], v[28:31]
	v_mfma_f32_16x16x32_bf16 v[24:27], v[140:143], v[164:167], v[24:27]
	v_mfma_f32_16x16x32_bf16 v[12:15], v[132:135], v[172:175], v[12:15]
	v_mfma_f32_16x16x32_bf16 v[8:11], v[140:143], v[172:175], v[8:11]
	v_mfma_f32_16x16x32_bf16 v[52:55], v[176:179], v[144:147], v[52:55]
	v_mfma_f32_16x16x32_bf16 v[48:51], v[222:225], v[144:147], v[48:51]
	v_mfma_f32_16x16x32_bf16 v[36:39], v[176:179], v[152:155], v[36:39]
	v_mfma_f32_16x16x32_bf16 v[32:35], v[222:225], v[152:155], v[32:35]
	v_mfma_f32_16x16x32_bf16 v[20:23], v[176:179], v[160:163], v[20:23]
	v_mfma_f32_16x16x32_bf16 v[16:19], v[222:225], v[160:163], v[16:19]
	v_mfma_f32_16x16x32_bf16 v[4:7], v[176:179], v[168:171], v[4:7]
	v_mfma_f32_16x16x32_bf16 v[0:3], v[222:225], v[168:171], v[0:3]
	v_mfma_f32_16x16x32_bf16 v[52:55], v[180:183], v[148:151], v[52:55]
	v_mfma_f32_16x16x32_bf16 v[48:51], v[226:229], v[148:151], v[48:51]
	v_mfma_f32_16x16x32_bf16 v[36:39], v[180:183], v[156:159], v[36:39]
	v_mfma_f32_16x16x32_bf16 v[32:35], v[226:229], v[156:159], v[32:35]
	v_mfma_f32_16x16x32_bf16 v[20:23], v[180:183], v[164:167], v[20:23]
	v_mfma_f32_16x16x32_bf16 v[16:19], v[226:229], v[164:167], v[16:19]
	v_mfma_f32_16x16x32_bf16 v[4:7], v[180:183], v[172:175], v[4:7]
	v_mfma_f32_16x16x32_bf16 v[0:3], v[226:229], v[172:175], v[0:3]
	s_setprio 0
	s_addk_i32 s79, 0x80
	s_add_u32 s6, s6, 0x100
	s_addc_u32 s7, s7, 0
	s_add_u32 s55, s55, 0x100
	s_addc_u32 s78, s78, 0
	s_cmp_ge_u32 s61, s65
	s_mov_b32 s60, s61
	s_barrier
	s_cbranch_scc1 .LBB0_470
	s_branch .LBB0_463

;     __device__ __forceinline__ void rescale(f32x4 (&acc)[2][2][4][2], const Unit& u, int which, int wr, int wc, int fr, int fq) const { EpiBranchCat e; e.gates = (const bf16_t*)d.q0; e.mb = nullptr; e.rescale(acc, u, which, wr, wc, fr, fq); }
; template <class Epi>
; __device__ __forceinline__ void gemm_phase(LAS unsigned char* lds, const Gemm g, const StaticOrder& S, const Epi& E, const bool perm) {
;     ...
;         for (int t = 0; t < nt; t += 2) {
;             if (E.hook() && (t == 8 || t == 16)) E.rescale(acc, cur, t >> 4, wr, wc, fr, fq);
.LBB0_463:
	s_cmp_eq_u32 s60, 0
	s_cbranch_scc1 .Lk_first
	s_andn2_b64 vcc, exec, s[18:19]
	s_cbranch_vccnz .LBB0_462
	s_cmp_lt_i32 s60, 16
	s_cbranch_scc1 .LBB0_466
	s_cmp_eq_u32 s60, 16
	s_cselect_b64 s[22:23], -1, 0
	s_cbranch_execz .LBB0_467
	s_branch .LBB0_468
